# opt28: wave 1 of every workgroup issues an un-waited buffer_wbl2 at grid-barrier entry (early write-back, nobody blocks on it); on v068
# baseline (speedup 1.0000x reference)
.LBB0_133:
	s_cmp_eq_u32 s75, 2
	s_cbranch_scc1 .LBB0_187
	s_waitcnt vmcnt(0)
	s_barrier
	s_cmp_eq_u32 s91, 1
	s_cbranch_scc0 .Lmy_ewb_1
	buffer_wbl2 sc1
.Lmy_ewb_1:
	s_and_saveexec_b64 s[0:1], s[92:93]
	s_cbranch_execz .LBB0_186
	s_add_i32 s3, 0, 0x27fc0
	v_mov_b32_e32 v0, s3
	s_waitcnt vmcnt(0) expcnt(0) lgkmcnt(0)
	ds_read_b32 v2, v0
	s_add_i32 s3, 0, 0x27fc4
	v_mov_b32_e32 v0, s3
	ds_read_b32 v0, v0
	s_waitcnt lgkmcnt(1)
	v_cmp_ne_u32_e32 vcc, 0, v2
	s_cbranch_vccnz .LBB0_150
	s_add_u32 s4, s70, 0x4200
	s_addc_u32 s5, s71, 0
	s_add_u32 s6, s70, 0x4400
	s_addc_u32 s7, s71, 0
	s_add_u32 s8, s70, 0x4500
	s_addc_u32 s9, s71, 0
	s_add_u32 s10, s70, 0x4600
	s_addc_u32 s11, s71, 0
	s_add_u32 s14, s70, 0x4700
	s_addc_u32 s15, s71, 0
	s_add_u32 s16, s70, 0x4800
	s_addc_u32 s17, s71, 0
	s_add_u32 s18, s70, 0x4900
	s_addc_u32 s19, s71, 0
	s_add_u32 s20, s70, 0x4a00
	s_addc_u32 s21, s71, 0
	s_add_u32 s22, s70, 0x4b00
	s_addc_u32 s23, s71, 0
	s_add_u32 s26, s70, 0x4c00
	s_addc_u32 s27, s71, 0
	s_add_u32 s28, s70, 0x4d00
	s_addc_u32 s29, s71, 0
	s_add_u32 s40, s70, 0x4e00
	s_addc_u32 s41, s71, 0
	s_add_u32 s42, s70, 0x4f00
	s_addc_u32 s43, s71, 0
	s_add_u32 s48, s70, 0x5000
	s_addc_u32 s49, s71, 0
	s_add_u32 s50, s70, 0x5100
	s_addc_u32 s51, s71, 0
	s_add_u32 s52, s70, 0x5200
	s_addc_u32 s53, s71, 0
	s_mul_i32 s3, s73, s96
	s_add_u32 s54, s70, 0x5300
	s_mul_i32 s3, s3, s72
	s_addc_u32 s55, s71, 0
	s_mov_b32 s12, 1
	v_mov_b32_e32 v16, 0
	s_branch .LBB0_138

.LBB0_250:
	s_waitcnt vmcnt(0)
	s_waitcnt vmcnt(0) lgkmcnt(0)
	s_barrier
	s_cmp_eq_u32 s91, 1
	s_cbranch_scc0 .Lmy_ewb_2
	buffer_wbl2 sc1
.Lmy_ewb_2:
	s_and_saveexec_b64 s[0:1], s[92:93]
	s_cbranch_execz .LBB0_302
	s_add_i32 s3, 0, 0x27fc0
	v_mov_b32_e32 v0, s3
	s_waitcnt vmcnt(0) expcnt(0) lgkmcnt(0)
	ds_read_b32 v2, v0
	s_add_i32 s3, 0, 0x27fc4
	v_mov_b32_e32 v0, s3
	ds_read_b32 v0, v0
	s_waitcnt lgkmcnt(1)
	v_cmp_ne_u32_e32 vcc, 0, v2
	s_cbranch_vccnz .LBB0_266
	s_add_u32 s4, s70, 0x4200
	s_addc_u32 s5, s71, 0
	s_add_u32 s6, s70, 0x4400
	s_addc_u32 s7, s71, 0
	s_add_u32 s8, s70, 0x4500
	s_addc_u32 s9, s71, 0
	s_add_u32 s10, s70, 0x4600
	s_addc_u32 s11, s71, 0
	s_add_u32 s20, s70, 0x4700
	s_addc_u32 s21, s71, 0
	s_add_u32 s22, s70, 0x4800
	s_addc_u32 s23, s71, 0
	s_add_u32 s26, s70, 0x4900
	s_addc_u32 s27, s71, 0
	s_add_u32 s28, s70, 0x4a00
	s_addc_u32 s29, s71, 0
	s_add_u32 s40, s70, 0x4b00
	s_addc_u32 s41, s71, 0
	s_add_u32 s42, s70, 0x4c00
	s_addc_u32 s43, s71, 0
	s_add_u32 s48, s70, 0x4d00
	s_addc_u32 s49, s71, 0
	s_add_u32 s50, s70, 0x4e00
	s_addc_u32 s51, s71, 0
	s_add_u32 s52, s70, 0x4f00
	s_addc_u32 s53, s71, 0
	s_add_u32 s54, s70, 0x5000
	s_addc_u32 s55, s71, 0
	s_add_u32 s56, s70, 0x5100
	s_addc_u32 s57, s71, 0
	s_add_u32 s58, s70, 0x5200
	s_addc_u32 s59, s71, 0
	s_mul_i32 s3, s73, s96
	s_add_u32 s62, s70, 0x5300
	s_mul_i32 s3, s3, s72
	s_addc_u32 s63, s71, 0
	s_mov_b32 s12, 1
	v_mov_b32_e32 v16, 0
	s_branch .LBB0_254

.LBB0_311:
	s_or_b64 exec, exec, s[0:1]
	s_cmp_eq_u32 s75, 4
	s_cbranch_scc1 .LBB0_365
	s_waitcnt vmcnt(0)
	s_waitcnt vmcnt(0) lgkmcnt(0)
	s_barrier
	s_cmp_eq_u32 s91, 1
	s_cbranch_scc0 .Lmy_ewb_3
	buffer_wbl2 sc1
.Lmy_ewb_3:
	s_and_saveexec_b64 s[0:1], s[92:93]
	s_cbranch_execz .LBB0_364
	s_add_i32 s3, 0, 0x27fc0
	v_mov_b32_e32 v0, s3
	s_waitcnt vmcnt(0) expcnt(0) lgkmcnt(0)
	ds_read_b32 v2, v0
	s_add_i32 s3, 0, 0x27fc4
	v_mov_b32_e32 v0, s3
	ds_read_b32 v0, v0
	s_waitcnt lgkmcnt(1)
	v_cmp_ne_u32_e32 vcc, 0, v2
	s_cbranch_vccnz .LBB0_328
	s_add_u32 s4, s70, 0x4200
	s_addc_u32 s5, s71, 0
	s_add_u32 s6, s70, 0x4400
	s_addc_u32 s7, s71, 0
	s_add_u32 s8, s70, 0x4500
	s_addc_u32 s9, s71, 0
	s_add_u32 s10, s70, 0x4600
	s_addc_u32 s11, s71, 0
	s_add_u32 s22, s70, 0x4700
	s_addc_u32 s23, s71, 0
	s_add_u32 s26, s70, 0x4800
	s_addc_u32 s27, s71, 0
	s_add_u32 s28, s70, 0x4900
	s_addc_u32 s29, s71, 0
	s_add_u32 s40, s70, 0x4a00
	s_addc_u32 s41, s71, 0
	s_add_u32 s42, s70, 0x4b00
	s_addc_u32 s43, s71, 0
	s_add_u32 s48, s70, 0x4c00
	s_addc_u32 s49, s71, 0
	s_add_u32 s50, s70, 0x4d00
	s_addc_u32 s51, s71, 0
	s_add_u32 s52, s70, 0x4e00
	s_addc_u32 s53, s71, 0
	s_add_u32 s54, s70, 0x4f00
	s_addc_u32 s55, s71, 0
	s_add_u32 s56, s70, 0x5000
	s_addc_u32 s57, s71, 0
	s_add_u32 s58, s70, 0x5100
	s_addc_u32 s59, s71, 0
	s_add_u32 s62, s70, 0x5200
	s_addc_u32 s63, s71, 0
	s_mul_i32 s3, s73, s96
	s_add_u32 s64, s70, 0x5300
	s_mul_i32 s3, s3, s72
	s_addc_u32 s65, s71, 0
	s_mov_b32 s12, 1
	v_mov_b32_e32 v16, 0
	s_branch .LBB0_316

.LBB0_483:
	s_cmp_eq_u32 s75, 6
	s_cbranch_scc1 .LBB0_537
	s_waitcnt vmcnt(0)
	s_waitcnt vmcnt(0)
	s_barrier
	s_cmp_eq_u32 s91, 1
	s_cbranch_scc0 .Lmy_ewb_5
	buffer_wbl2 sc1

.LBB0_894:
	s_cmp_eq_u32 s75, 9
	s_cbranch_scc1 .LBB0_948
	s_waitcnt vmcnt(0)
	s_waitcnt vmcnt(0) lgkmcnt(0)
	s_barrier
	s_cmp_eq_u32 s91, 1
	s_cbranch_scc0 .Lmy_ewb_8
	buffer_wbl2 sc1
.Lmy_ewb_8:
	s_and_saveexec_b64 s[0:1], s[92:93]
	s_cbranch_execz .LBB0_947
	s_add_i32 s3, 0, 0x27fc0
	v_mov_b32_e32 v0, s3
	s_waitcnt vmcnt(0) expcnt(0) lgkmcnt(0)
	ds_read_b32 v2, v0
	s_add_i32 s3, 0, 0x27fc4
	v_mov_b32_e32 v0, s3
	ds_read_b32 v0, v0
	s_waitcnt lgkmcnt(1)
	v_cmp_ne_u32_e32 vcc, 0, v2
	s_cbranch_vccnz .LBB0_911
	s_add_u32 s4, s70, 0x4200
	s_addc_u32 s5, s71, 0
	s_add_u32 s6, s70, 0x4400
	s_addc_u32 s7, s71, 0
	s_add_u32 s8, s70, 0x4500
	s_addc_u32 s9, s71, 0
	s_add_u32 s10, s70, 0x4600
	s_addc_u32 s11, s71, 0
	s_add_u32 s22, s70, 0x4700
	s_addc_u32 s23, s71, 0
	s_add_u32 s26, s70, 0x4800
	s_addc_u32 s27, s71, 0
	s_add_u32 s28, s70, 0x4900
	s_addc_u32 s29, s71, 0
	s_add_u32 s30, s70, 0x4a00
	s_addc_u32 s31, s71, 0
	s_add_u32 s36, s70, 0x4b00
	s_addc_u32 s37, s71, 0
	s_add_u32 s38, s70, 0x4c00
	s_addc_u32 s39, s71, 0
	s_add_u32 s40, s70, 0x4d00
	s_addc_u32 s41, s71, 0
	s_add_u32 s42, s70, 0x4e00
	s_addc_u32 s43, s71, 0
	s_add_u32 s48, s70, 0x4f00
	s_addc_u32 s49, s71, 0
	s_add_u32 s50, s70, 0x5000
	s_addc_u32 s51, s71, 0
	s_add_u32 s52, s70, 0x5100
	s_addc_u32 s53, s71, 0
	s_add_u32 s54, s70, 0x5200
	s_addc_u32 s55, s71, 0
	s_mul_i32 s3, s73, s96
	s_add_u32 s56, s70, 0x5300
	s_mul_i32 s3, s3, s72
	s_addc_u32 s57, s71, 0
	s_mov_b32 s12, 1
	v_mov_b32_e32 v16, 0
	s_branch .LBB0_899

.LBB0_1066:
	s_cmp_eq_u32 s75, 11
	s_cbranch_scc1 .LBB0_1120
	s_waitcnt vmcnt(0)
	s_waitcnt vmcnt(0)
	s_barrier
	s_cmp_eq_u32 s91, 1
	s_cbranch_scc0 .Lmy_ewb_10
	buffer_wbl2 sc1

.LBB0_1242:
	s_cmp_eq_u32 s75, 13
	s_cbranch_scc1 .LBB0_1296
	s_waitcnt vmcnt(0)
	s_waitcnt vmcnt(0)
	s_barrier
	s_cmp_eq_u32 s91, 1
	s_cbranch_scc0 .Lmy_ewb_12
	buffer_wbl2 sc1

.LBB0_1346:
	s_cmp_eq_u32 s75, 14
	s_cbranch_scc1 .LBB0_1400
	s_waitcnt vmcnt(0)
	s_waitcnt vmcnt(0) lgkmcnt(0)
	s_barrier
	s_cmp_eq_u32 s91, 1
	s_cbranch_scc0 .Lmy_ewb_13
	buffer_wbl2 sc1
.Lmy_ewb_13:
	s_and_saveexec_b64 s[0:1], s[92:93]
	s_cbranch_execz .LBB0_1399
	s_add_i32 s3, 0, 0x27fc0
	v_mov_b32_e32 v0, s3
	s_waitcnt vmcnt(0) expcnt(0) lgkmcnt(0)
	ds_read_b32 v2, v0
	s_add_i32 s3, 0, 0x27fc4
	v_mov_b32_e32 v0, s3
	ds_read_b32 v0, v0
	s_waitcnt lgkmcnt(1)
	v_cmp_ne_u32_e32 vcc, 0, v2
	s_cbranch_vccnz .LBB0_1363
	s_add_u32 s4, s70, 0x4200
	s_addc_u32 s5, s71, 0
	s_add_u32 s6, s70, 0x4400
	s_addc_u32 s7, s71, 0
	s_add_u32 s10, s70, 0x4500
	s_addc_u32 s11, s71, 0
	s_add_u32 s22, s70, 0x4600
	s_addc_u32 s23, s71, 0
	s_add_u32 s26, s70, 0x4700
	s_addc_u32 s27, s71, 0
	s_add_u32 s28, s70, 0x4800
	s_addc_u32 s29, s71, 0
	s_add_u32 s30, s70, 0x4900
	s_addc_u32 s31, s71, 0
	s_add_u32 s36, s70, 0x4a00
	s_addc_u32 s37, s71, 0
	s_add_u32 s38, s70, 0x4b00
	s_addc_u32 s39, s71, 0
	s_add_u32 s40, s70, 0x4c00
	s_addc_u32 s41, s71, 0
	s_add_u32 s42, s70, 0x4d00
	s_addc_u32 s43, s71, 0
	s_add_u32 s48, s70, 0x4e00
	s_addc_u32 s49, s71, 0
	s_add_u32 s50, s70, 0x4f00
	s_addc_u32 s51, s71, 0
	s_add_u32 s52, s70, 0x5000
	s_addc_u32 s53, s71, 0
	s_add_u32 s54, s70, 0x5100
	s_addc_u32 s55, s71, 0
	s_add_u32 s56, s70, 0x5200
	s_addc_u32 s57, s71, 0
	s_mul_i32 s3, s73, s96
	s_add_u32 s58, s70, 0x5300
	s_mul_i32 s3, s3, s72
	s_addc_u32 s59, s71, 0
	s_mov_b32 s12, 1
	v_mov_b32_e32 v16, 0
	s_branch .LBB0_1351

.LBB0_1420:
	s_cmp_eq_u32 s75, 15
	s_cbranch_scc1 .LBB0_1474
	s_waitcnt vmcnt(0)
	s_waitcnt vmcnt(0) lgkmcnt(0)
	s_barrier
	s_cmp_eq_u32 s91, 1
	s_cbranch_scc0 .Lmy_ewb_14
	buffer_wbl2 sc1

.LBB0_1482:
	s_cmp_eq_u32 s75, 16
	s_cbranch_scc1 .LBB0_1536
	s_waitcnt vmcnt(0)
	s_waitcnt vmcnt(0) lgkmcnt(0)
	s_barrier
	s_cmp_eq_u32 s91, 1
	s_cbranch_scc0 .Lmy_ewb_15
	buffer_wbl2 sc1
.Lmy_ewb_15:
	s_and_saveexec_b64 s[0:1], s[92:93]
	s_cbranch_execz .LBB0_1535
	s_add_i32 s3, 0, 0x27fc0
	v_mov_b32_e32 v0, s3
	s_waitcnt vmcnt(0) expcnt(0) lgkmcnt(0)
	ds_read_b32 v2, v0
	s_add_i32 s3, 0, 0x27fc4
	v_mov_b32_e32 v0, s3
	ds_read_b32 v0, v0
	s_waitcnt lgkmcnt(1)
	v_cmp_ne_u32_e32 vcc, 0, v2
	s_cbranch_vccnz .LBB0_1499
	s_add_u32 s4, s70, 0x4200
	s_addc_u32 s5, s71, 0
	s_add_u32 s6, s70, 0x4400
	s_addc_u32 s7, s71, 0
	s_add_u32 s8, s70, 0x4500
	s_addc_u32 s9, s71, 0
	s_add_u32 s10, s70, 0x4600
	s_addc_u32 s11, s71, 0
	s_add_u32 s22, s70, 0x4700
	s_addc_u32 s23, s71, 0
	s_add_u32 s26, s70, 0x4800
	s_addc_u32 s27, s71, 0
	s_add_u32 s28, s70, 0x4900
	s_addc_u32 s29, s71, 0
	s_add_u32 s30, s70, 0x4a00
	s_addc_u32 s31, s71, 0
	s_add_u32 s36, s70, 0x4b00
	s_addc_u32 s37, s71, 0
	s_add_u32 s38, s70, 0x4c00
	s_addc_u32 s39, s71, 0
	s_add_u32 s40, s70, 0x4d00
	s_addc_u32 s41, s71, 0
	s_add_u32 s42, s70, 0x4e00
	s_addc_u32 s43, s71, 0
	s_add_u32 s44, s70, 0x4f00
	s_addc_u32 s45, s71, 0
	s_add_u32 s46, s70, 0x5000
	s_addc_u32 s47, s71, 0
	s_add_u32 s48, s70, 0x5100
	s_addc_u32 s49, s71, 0
	s_add_u32 s50, s70, 0x5200
	s_addc_u32 s51, s71, 0
	s_mul_i32 s3, s73, s96
	s_add_u32 s52, s70, 0x5300
	s_mul_i32 s3, s3, s72
	s_addc_u32 s53, s71, 0
	s_mov_b32 s12, 1
	v_mov_b32_e32 v16, 0
	s_branch .LBB0_1487

.LBB0_1654:
	s_cmp_eq_u32 s75, 18
	s_cbranch_scc1 .LBB0_1708
	s_waitcnt vmcnt(0)
	s_waitcnt vmcnt(0)
	s_barrier
	s_cmp_eq_u32 s91, 1
	s_cbranch_scc0 .Lmy_ewb_17
	buffer_wbl2 sc1

.LBB0_1926:
	s_or_b64 exec, exec, s[0:1]
	s_cmp_eq_u32 s75, 21
	s_cbranch_scc1 .LBB0_1980
	s_waitcnt vmcnt(0)
	s_waitcnt vmcnt(0) lgkmcnt(0)
	s_barrier
	s_cmp_eq_u32 s91, 1
	s_cbranch_scc0 .Lmy_ewb_20
	buffer_wbl2 sc1
.Lmy_ewb_20:
	s_and_saveexec_b64 s[0:1], s[92:93]
	s_cbranch_execz .LBB0_1979
	s_add_i32 s3, 0, 0x27fc0
	v_mov_b32_e32 v0, s3
	s_waitcnt vmcnt(0) expcnt(0) lgkmcnt(0)
	ds_read_b32 v2, v0
	s_add_i32 s3, 0, 0x27fc4
	v_mov_b32_e32 v0, s3
	ds_read_b32 v0, v0
	s_waitcnt lgkmcnt(1)
	v_cmp_ne_u32_e32 vcc, 0, v2
	s_cbranch_vccnz .LBB0_1943
	s_add_u32 s4, s70, 0x4200
	s_addc_u32 s5, s71, 0
	s_add_u32 s6, s70, 0x4400
	s_addc_u32 s7, s71, 0
	s_add_u32 s8, s70, 0x4500
	s_addc_u32 s9, s71, 0
	s_add_u32 s10, s70, 0x4600
	s_addc_u32 s11, s71, 0
	s_add_u32 s22, s70, 0x4700
	s_addc_u32 s23, s71, 0
	s_add_u32 s24, s70, 0x4800
	s_addc_u32 s25, s71, 0
	s_add_u32 s26, s70, 0x4900
	s_addc_u32 s27, s71, 0
	s_add_u32 s28, s70, 0x4a00
	s_addc_u32 s29, s71, 0
	s_add_u32 s30, s70, 0x4b00
	s_addc_u32 s31, s71, 0
	s_add_u32 s36, s70, 0x4c00
	s_addc_u32 s37, s71, 0
	s_add_u32 s38, s70, 0x4d00
	s_addc_u32 s39, s71, 0
	s_add_u32 s40, s70, 0x4e00
	s_addc_u32 s41, s71, 0
	s_add_u32 s42, s70, 0x4f00
	s_addc_u32 s43, s71, 0
	s_add_u32 s44, s70, 0x5000
	s_addc_u32 s45, s71, 0
	s_add_u32 s46, s70, 0x5100
	s_addc_u32 s47, s71, 0
	s_add_u32 s48, s70, 0x5200
	s_addc_u32 s49, s71, 0
	s_mul_i32 s3, s73, s96
	s_add_u32 s50, s70, 0x5300
	s_mul_i32 s3, s3, s72
	s_addc_u32 s51, s71, 0
	s_mov_b32 s12, 1
	v_mov_b32_e32 v16, 0
	s_branch .LBB0_1931

.Lmy_ewb_21:
	s_and_saveexec_b64 s[0:1], s[92:93]
	s_cbranch_execz .LBB0_2076
	s_add_i32 s3, 0, 0x27fc0
	v_mov_b32_e32 v0, s3
	s_waitcnt vmcnt(0) expcnt(0) lgkmcnt(0)
	ds_read_b32 v2, v0
	s_add_i32 s3, 0, 0x27fc4
	v_mov_b32_e32 v0, s3
	ds_read_b32 v0, v0
	s_waitcnt lgkmcnt(1)
	v_cmp_ne_u32_e32 vcc, 0, v2
	s_cbranch_vccnz .LBB0_2040
	s_add_u32 s4, s70, 0x4200
	s_addc_u32 s5, s71, 0
	s_add_u32 s6, s70, 0x4400
	s_addc_u32 s7, s71, 0
	s_add_u32 s8, s70, 0x4500
	s_addc_u32 s9, s71, 0
	s_add_u32 s10, s70, 0x4600
	s_addc_u32 s11, s71, 0
	s_add_u32 s20, s70, 0x4700
	s_addc_u32 s21, s71, 0
	s_add_u32 s22, s70, 0x4800
	s_addc_u32 s23, s71, 0
	s_add_u32 s24, s70, 0x4900
	s_addc_u32 s25, s71, 0
	s_add_u32 s26, s70, 0x4a00
	s_addc_u32 s27, s71, 0
	s_add_u32 s28, s70, 0x4b00
	s_addc_u32 s29, s71, 0
	s_add_u32 s30, s70, 0x4c00
	s_addc_u32 s31, s71, 0
	s_add_u32 s36, s70, 0x4d00
	s_addc_u32 s37, s71, 0
	s_add_u32 s38, s70, 0x4e00
	s_addc_u32 s39, s71, 0
	s_add_u32 s40, s70, 0x4f00
	s_addc_u32 s41, s71, 0
	s_add_u32 s42, s70, 0x5000
	s_addc_u32 s43, s71, 0
	s_add_u32 s44, s70, 0x5100
	s_addc_u32 s45, s71, 0
	s_add_u32 s46, s70, 0x5200
	s_addc_u32 s47, s71, 0
	s_mul_i32 s3, s73, s96
	s_add_u32 s48, s70, 0x5300
	s_mul_i32 s3, s3, s72
	s_addc_u32 s49, s71, 0
	s_mov_b32 s12, 1
	v_mov_b32_e32 v16, 0
	s_branch .LBB0_2028

.LBB0_2098:
	s_cmp_eq_u32 s75, 23
	s_cbranch_scc1 .LBB0_2152
	s_waitcnt vmcnt(0)
	s_waitcnt vmcnt(0)
	s_barrier
	s_cmp_eq_u32 s91, 1
	s_cbranch_scc0 .Lmy_ewb_22
	buffer_wbl2 sc1
.Lmy_ewb_22:
	s_and_saveexec_b64 s[0:1], s[92:93]
	s_cbranch_execz .LBB0_2151
	s_add_i32 s3, 0, 0x27fc0
	v_mov_b32_e32 v0, s3
	s_waitcnt vmcnt(0) expcnt(0) lgkmcnt(0)
	ds_read_b32 v2, v0
	s_add_i32 s3, 0, 0x27fc4
	v_mov_b32_e32 v0, s3
	ds_read_b32 v0, v0
	s_waitcnt lgkmcnt(1)
	v_cmp_ne_u32_e32 vcc, 0, v2
	s_cbranch_vccnz .LBB0_2115
	s_add_u32 s4, s70, 0x4200
	s_addc_u32 s5, s71, 0
	s_add_u32 s6, s70, 0x4400
	s_addc_u32 s7, s71, 0
	s_add_u32 s8, s70, 0x4500
	s_addc_u32 s9, s71, 0
	s_add_u32 s10, s70, 0x4600
	s_addc_u32 s11, s71, 0
	s_add_u32 s18, s70, 0x4700
	s_addc_u32 s19, s71, 0
	s_add_u32 s20, s70, 0x4800
	s_addc_u32 s21, s71, 0
	s_add_u32 s22, s70, 0x4900
	s_addc_u32 s23, s71, 0
	s_add_u32 s24, s70, 0x4a00
	s_addc_u32 s25, s71, 0
	s_add_u32 s26, s70, 0x4b00
	s_addc_u32 s27, s71, 0
	s_add_u32 s28, s70, 0x4c00
	s_addc_u32 s29, s71, 0
	s_add_u32 s30, s70, 0x4d00
	s_addc_u32 s31, s71, 0
	s_add_u32 s36, s70, 0x4e00
	s_addc_u32 s37, s71, 0
	s_add_u32 s38, s70, 0x4f00
	s_addc_u32 s39, s71, 0
	s_add_u32 s40, s70, 0x5000
	s_addc_u32 s41, s71, 0
	s_add_u32 s42, s70, 0x5100
	s_addc_u32 s43, s71, 0
	s_add_u32 s44, s70, 0x5200
	s_addc_u32 s45, s71, 0
	s_mul_i32 s3, s73, s96
	s_add_u32 s46, s70, 0x5300
	s_mul_i32 s3, s3, s72
	s_addc_u32 s47, s71, 0
	s_mov_b32 s12, 1
	v_mov_b32_e32 v16, 0
	s_branch .LBB0_2103

.LBB0_2181:
	s_cmp_eq_u32 s75, 24
	s_cbranch_scc1 .LBB0_2235
	s_waitcnt vmcnt(0)
	s_waitcnt vmcnt(0) lgkmcnt(0)
	s_barrier
	s_cmp_eq_u32 s91, 1
	s_cbranch_scc0 .Lmy_ewb_23
	buffer_wbl2 sc1
.Lmy_ewb_23:
	s_and_saveexec_b64 s[0:1], s[92:93]
	s_cbranch_execz .LBB0_2234
	s_add_i32 s2, 0, 0x27fc0
	v_mov_b32_e32 v0, s2
	s_waitcnt vmcnt(0) expcnt(0) lgkmcnt(0)
	ds_read_b32 v2, v0
	s_add_i32 s2, 0, 0x27fc4
	v_mov_b32_e32 v0, s2
	ds_read_b32 v0, v0
	s_waitcnt lgkmcnt(1)
	v_cmp_ne_u32_e32 vcc, 0, v2
	s_cbranch_vccnz .LBB0_2198
	s_add_u32 s2, s70, 0x4200
	s_addc_u32 s3, s71, 0
	s_add_u32 s4, s70, 0x4400
	s_addc_u32 s5, s71, 0
	s_add_u32 s6, s70, 0x4500
	s_addc_u32 s7, s71, 0
	s_add_u32 s8, s70, 0x4600
	s_addc_u32 s9, s71, 0
	s_add_u32 s10, s70, 0x4700
	s_addc_u32 s11, s71, 0
	s_add_u32 s12, s70, 0x4800
	s_addc_u32 s13, s71, 0
	s_add_u32 s14, s70, 0x4900
	s_addc_u32 s15, s71, 0
	s_add_u32 s16, s70, 0x4a00
	s_addc_u32 s17, s71, 0
	s_add_u32 s18, s70, 0x4b00
	s_addc_u32 s19, s71, 0
	s_add_u32 s20, s70, 0x4c00
	s_addc_u32 s21, s71, 0
	s_add_u32 s22, s70, 0x4d00
	s_addc_u32 s23, s71, 0
	s_add_u32 s24, s70, 0x4e00
	s_addc_u32 s25, s71, 0
	s_add_u32 s26, s70, 0x4f00
	s_addc_u32 s27, s71, 0
	s_add_u32 s28, s70, 0x5000
	s_addc_u32 s29, s71, 0
	s_add_u32 s30, s70, 0x5100
	s_addc_u32 s31, s71, 0
	s_add_u32 s36, s70, 0x5200
	s_addc_u32 s37, s71, 0
	s_mul_i32 s34, s73, s96
	s_add_u32 s38, s70, 0x5300
	s_mul_i32 s34, s34, s72
	s_addc_u32 s39, s71, 0
	s_mov_b32 s35, 1
	v_mov_b32_e32 v16, 0
	s_branch .LBB0_2186
